# fast path v16 = v15 + next-iteration LDS read bases computed in the last MFMA gap instead of after the last MFMA
# speedup vs baseline: 1.0116x; 1.0006x over previous
; #define MFMA32(a, b, c) __builtin_amdgcn_mfma_f32_32x32x16_bf16((a), (b), (c), 0, 0, 0)
; DI unsigned pk_bf16(float lo, float hi) { f32x2 v = {lo, hi}; bf16v2 b = __builtin_convertvector(v, bf16v2); return __builtin_bit_cast(unsigned, b); }
; DI int crow(int r, int h) { return (r & 3) + 8 * (r >> 2) + 4 * h; }
; DI void attn_item(const Params& p, int g, int seq, int hd, int qt, int m, char* smem, int split_j, int sub) {
;     ...
;     bf16x8 kf[4], vf[2][4];
; #pragma unroll
;     for (int s = 0; s < 4; ++s) kf[s] = *(const bf16x8*)(Kb + l31 * 72 + s * 16 + h * 8);
; #pragma unroll
;     for (int s2 = 0; s2 < 2; ++s2)
; #pragma unroll
;       for (int dt = 0; dt < 4; ++dt) vf[s2][dt] = *(const bf16x8*)(Vb + (dt * 32 + l31) * 40 + s2 * 16 + h * 8);
;     __builtin_amdgcn_sched_barrier(0);
;     f32x16 X;
; #pragma unroll
;     for (int r = 0; r < 16; ++r) X[r] = 0.f;
; #pragma unroll
;     for (int s = 0; s < 4; ++s) X = MFMA32(kf[s], qf[s], X);
;     if (farL || farR) {
; #pragma unroll
;       for (int r = 0; r < 16; ++r) X[r] = __builtin_amdgcn_exp2f(X[r]);
;     } else {
;       const int rel0 = k0 - (qw0 + l31) + 128;
; #pragma unroll
;       for (int r = 0; r < 16; ++r) { int idx = rel0 + crow(r, h); idx = idx < 0 ? 0 : (idx > 256 ? 256 : idx); X[r] = __builtin_amdgcn_exp2f(X[r] + tab[idx]); }
;     }
;     bf16x8 pf[2];
; #pragma unroll
;     for (int s2 = 0; s2 < 2; ++s2) {
;       u32x4 w; w.x = pk_bf16(X[8 * s2], X[8 * s2 + 1]); w.y = pk_bf16(X[8 * s2 + 2], X[8 * s2 + 3]); w.z = pk_bf16(X[8 * s2 + 4], X[8 * s2 + 5]); w.w = pk_bf16(X[8 * s2 + 6], X[8 * s2 + 7]);
;       ls2 += (f32x2){X[8 * s2], X[8 * s2 + 1]}; ls2 += (f32x2){X[8 * s2 + 2], X[8 * s2 + 3]};
;       ls2 += (f32x2){X[8 * s2 + 4], X[8 * s2 + 5]}; ls2 += (f32x2){X[8 * s2 + 6], X[8 * s2 + 7]};
;       pf[s2] = __builtin_bit_cast(bf16x8, w);
;     }
; #pragma unroll
;     for (int s2 = 0; s2 < 2; ++s2)
; #pragma unroll
;       for (int dt = 0; dt < 4; ++dt) O[dt] = MFMA32(pf[s2], vf[s2][dt], O[dt]);
.Lat2_reads:
	ds_read_b128 v[64:67], v192
	ds_read_b128 v[80:83], v192 offset:32
	ds_read_b128 v[84:87], v192 offset:64
	ds_read_b128 v[88:91], v192 offset:96
	s_waitcnt lgkmcnt(3)
	v_mfma_f32_32x32x16_bf16 v[64:79], v[64:67], v[104:107], 0
	ds_read_b128 v[220:223], v192 offset:4608
	ds_read_b128 v[224:227], v192 offset:4640
	ds_read_b128 v[236:239], v192 offset:4672
	ds_read_b128 v[240:243], v192 offset:4704
	s_waitcnt lgkmcnt(6)
	v_mfma_f32_32x32x16_bf16 v[64:79], v[80:83], v[108:111], v[64:79]
	ds_read_b128 v[156:159], v244 offset:18432
	ds_read_b128 v[160:163], v244 offset:20992
	s_waitcnt lgkmcnt(7)
	v_mfma_f32_32x32x16_bf16 v[64:79], v[84:87], v[112:115], v[64:79]
	ds_read_b128 v[164:167], v244 offset:23552
	ds_read_b128 v[152:155], v244 offset:26112
	s_waitcnt lgkmcnt(8)
	v_mfma_f32_32x32x16_bf16 v[64:79], v[88:91], v[116:119], v[64:79]
	ds_read_b128 v[148:151], v244 offset:18464
	ds_read_b128 v[144:147], v244 offset:21024
	ds_read_b128 v[136:139], v244 offset:23584
	ds_read_b128 v[140:143], v244 offset:26144
	s_waitcnt lgkmcnt(8)
	v_mfma_f32_32x32x16_bf16 v[80:95], v[220:223], v[104:107], 0
	v_mfma_f32_32x32x16_bf16 v[80:95], v[224:227], v[108:111], v[80:95]
	v_exp_f32_e32 v64, v64
	v_exp_f32_e32 v65, v65
	v_exp_f32_e32 v66, v66
	v_exp_f32_e32 v67, v67
	v_exp_f32_e32 v68, v68
	v_exp_f32_e32 v69, v69
	v_mfma_f32_32x32x16_bf16 v[80:95], v[236:239], v[112:115], v[80:95]
	v_exp_f32_e32 v70, v70
	v_exp_f32_e32 v71, v71
	v_exp_f32_e32 v72, v72
	v_exp_f32_e32 v73, v73
	v_exp_f32_e32 v74, v74
	v_exp_f32_e32 v75, v75
	v_mfma_f32_32x32x16_bf16 v[80:95], v[240:243], v[116:119], v[80:95]
	v_exp_f32_e32 v76, v76
	v_exp_f32_e32 v77, v77
	v_exp_f32_e32 v78, v78
	v_exp_f32_e32 v79, v79
	v_cvt_pk_bf16_f32 v220, v64, v65
	v_cvt_pk_bf16_f32 v221, v66, v67
	v_cvt_pk_bf16_f32 v222, v68, v69
	v_cvt_pk_bf16_f32 v223, v70, v71
	v_cvt_pk_bf16_f32 v224, v72, v73
	v_cvt_pk_bf16_f32 v225, v74, v75
	v_cvt_pk_bf16_f32 v226, v76, v77
	v_cvt_pk_bf16_f32 v227, v78, v79
	s_waitcnt lgkmcnt(0)
	v_mfma_f32_32x32x16_bf16 v[48:63], v[220:223], v[156:159], v[48:63]
	ds_read_b128 v[156:159], v244 offset:28672
	v_exp_f32_e32 v80, v80
	v_exp_f32_e32 v81, v81
	v_exp_f32_e32 v82, v82
	v_mfma_f32_32x32x16_bf16 v[32:47], v[220:223], v[160:163], v[32:47]
	ds_read_b128 v[160:163], v244 offset:31232
	v_exp_f32_e32 v83, v83
	v_exp_f32_e32 v84, v84
	v_exp_f32_e32 v85, v85
	v_mfma_f32_32x32x16_bf16 v[16:31], v[220:223], v[164:167], v[16:31]
	ds_read_b128 v[164:167], v244 offset:33792
	v_exp_f32_e32 v86, v86
	v_exp_f32_e32 v87, v87
	v_exp_f32_e32 v88, v88
	v_mfma_f32_32x32x16_bf16 v[0:15], v[220:223], v[152:155], v[0:15]
	ds_read_b128 v[152:155], v244 offset:36352
	v_exp_f32_e32 v89, v89
	v_exp_f32_e32 v90, v90
	v_exp_f32_e32 v91, v91
	v_mfma_f32_32x32x16_bf16 v[48:63], v[224:227], v[148:151], v[48:63]
	ds_read_b128 v[148:151], v244 offset:28704
	v_exp_f32_e32 v92, v92
	v_exp_f32_e32 v93, v93
	v_exp_f32_e32 v94, v94
	v_exp_f32_e32 v95, v95
	v_mfma_f32_32x32x16_bf16 v[32:47], v[224:227], v[144:147], v[32:47]
	ds_read_b128 v[144:147], v244 offset:31264
	v_cvt_pk_bf16_f32 v236, v80, v81
	v_cvt_pk_bf16_f32 v237, v82, v83
	v_cvt_pk_bf16_f32 v238, v84, v85
	v_add_f32_e32 v246, v66, v70
	v_add_f32_e32 v247, v67, v71
	v_add_f32_e32 v186, v186, v64
	v_add_f32_e32 v187, v187, v65
	v_mfma_f32_32x32x16_bf16 v[16:31], v[224:227], v[136:139], v[16:31]
	ds_read_b128 v[136:139], v244 offset:33824
	v_cvt_pk_bf16_f32 v239, v86, v87
	v_cvt_pk_bf16_f32 v240, v88, v89
	v_cvt_pk_bf16_f32 v241, v90, v91
	v_add_f32_e32 v246, v246, v74
	v_add_f32_e32 v247, v247, v75
	v_add_f32_e32 v186, v186, v68
	v_add_f32_e32 v187, v187, v69
	v_mfma_f32_32x32x16_bf16 v[0:15], v[224:227], v[140:143], v[0:15]
	ds_read_b128 v[140:143], v244 offset:36384
	v_cvt_pk_bf16_f32 v242, v92, v93
	v_cvt_pk_bf16_f32 v243, v94, v95
	v_add_f32_e32 v246, v246, v78
	v_add_f32_e32 v247, v247, v79
	v_add_f32_e32 v186, v186, v72
	v_add_f32_e32 v187, v187, v73
	s_andn2_b64 vcc, exec, s[8:9]
	s_cbranch_vccnz .Lat2_pvplain
; #define MFMA32(a, b, c) __builtin_amdgcn_mfma_f32_32x32x16_bf16((a), (b), (c), 0, 0, 0)
; DI void attn_item(const Params& p, int g, int seq, int hd, int qt, int m, char* smem, int split_j, int sub) {
;     ...
;     for (int s2 = 0; s2 < 2; ++s2)
; #pragma unroll
;       for (int dt = 0; dt < 4; ++dt) O[dt] = MFMA32(pf[s2], vf[s2][dt], O[dt]);
;   };
;   load_tile(0, rkA, rvA0, rvA1);
;   load_tile(1, rkB, rvB0, rvB1);
;   __syncthreads();
;   store_tile(0, rkA, rvA0, rvA1);
;   store_tile(1, rkB, rvB0, rvB1);
;   __syncthreads();
;   for (int it = 0; it < npairs; ++it) {
;     const int set = it & 1;
;     if (it + 1 < npairs) { load_tile(2 * it + 2, rkA, rvA0, rvA1); load_tile(2 * it + 3, rkB, rvB0, rvB1); }
;     compute(2 * it, 2 * set);
;     compute(2 * it + 1, 2 * set + 1);
;     if (it + 1 < npairs) { store_tile(2 * (set ^ 1), rkA, rvA0, rvA1); store_tile(2 * (set ^ 1) + 1, rkB, rvB0, rvB1); }
;     __syncthreads();
;   }
	s_add_i32 s10, s15, 1
	s_cmp_lt_u32 s10, s73
	s_cbranch_scc0 .Lat2_pvw
	s_xor_b32 s7, s16, 2
	s_mul_i32 s8, s7, 0x2800
	s_add_i32 s8, s8, 32
	s_mulk_i32 s7, 0x1200
	v_add_u32_e32 v192, s7, v169
	v_add3_u32 v244, s8, v189, v190
	s_addk_i32 s8, 0x2800
	s_add_i32 s13, s13, 64
	s_add_i32 s6, s6, 2
	s_mov_b32 s15, s10
	s_mov_b64 s[20:21], 0x2000
	s_waitcnt lgkmcnt(6)
	v_mfma_f32_32x32x16_bf16 v[48:63], v[236:239], v[156:159], v[48:63]
	s_waitcnt vmcnt(4)
	ds_write_b128 v192, v[96:99]
	s_add_i32 s50, s6, -1
	s_lshl_b64 s[10:11], s[50:51], 12
	s_add_u32 s10, s10, 0x800
	v_lshl_add_u64 v[220:221], v[172:173], 0, s[10:11]
	v_add_f32_e32 v186, v186, v76
	v_add_f32_e32 v187, v187, v77
	v_mfma_f32_32x32x16_bf16 v[32:47], v[236:239], v[160:163], v[32:47]
	ds_write_b128 v244, v[100:103] offset:18432
	global_load_dwordx4 v[96:99], v[220:221], off offset:-2048
	s_lshl_b64 s[10:11], s[50:51], 13
	s_add_u32 s10, s10, 0x800
	v_lshl_add_u64 v[222:223], v[170:171], 0, s[10:11]
	v_add_f32_e32 v186, v186, v246
	v_add_f32_e32 v187, v187, v247
	s_waitcnt lgkmcnt(6)
	v_mfma_f32_32x32x16_bf16 v[16:31], v[236:239], v[164:167], v[16:31]
	s_waitcnt vmcnt(3)
	ds_write_b128 v244, v[120:123] offset:23552
	global_load_dwordx4 v[100:103], v[222:223], off offset:-2048
	v_lshl_add_u64 v[224:225], v[222:223], 0, s[20:21]
	v_add_f32_e32 v246, v82, v86
	v_add_f32_e32 v247, v83, v87
	v_add_f32_e32 v186, v186, v80
	v_mfma_f32_32x32x16_bf16 v[0:15], v[236:239], v[152:155], v[0:15]
	ds_write_b128 v192, v[124:127] offset:4608
	global_load_dwordx4 v[120:123], v[222:223], off offset:2048
	v_add_f32_e32 v187, v187, v81
	v_add_f32_e32 v246, v246, v90
	v_add_f32_e32 v247, v247, v91
	s_waitcnt lgkmcnt(6)
	v_mfma_f32_32x32x16_bf16 v[48:63], v[240:243], v[148:151], v[48:63]
	v_add3_u32 v192, s8, v189, v190
	s_waitcnt vmcnt(3)
	ds_write_b128 v192, v[128:131] offset:18432
	global_load_dwordx4 v[124:127], v[220:221], off offset:2048
	v_add_f32_e32 v186, v186, v84
	v_add_f32_e32 v187, v187, v85
	v_add_f32_e32 v246, v246, v94
	v_mfma_f32_32x32x16_bf16 v[32:47], v[240:243], v[144:147], v[32:47]
	ds_write_b128 v192, v[132:135] offset:23552
	global_load_dwordx4 v[128:131], v[224:225], off offset:-2048
	v_add_f32_e32 v247, v247, v95
	v_add_f32_e32 v186, v186, v88
	v_add_f32_e32 v187, v187, v89
	s_waitcnt lgkmcnt(6)
	v_mfma_f32_32x32x16_bf16 v[16:31], v[240:243], v[136:139], v[16:31]
	global_load_dwordx4 v[132:135], v[224:225], off offset:2048
	v_add_f32_e32 v186, v186, v92
	v_add_f32_e32 v187, v187, v93
	s_add_i32 s7, s14, s13
	s_cmpk_lt_i32 s7, 0xff42
	s_cselect_b32 s19, 1, 0
	s_cmpk_gt_i32 s7, 0x9e
	s_cselect_b32 s50, 1, 0
	s_cmp_eq_u32 s17, 2
	s_cselect_b32 s50, s50, 0
	s_or_b32 s19, s19, s50
	s_add_i32 s10, s6, -3
	s_and_b32 s16, s10, 2
	s_mul_i32 s10, s16, 0x1200
	s_mul_i32 s18, s16, 0x2800
	v_add_u32_e32 v192, s10, v191
	v_add_u32_e32 v244, s18, v196
	v_mfma_f32_32x32x16_bf16 v[0:15], v[240:243], v[140:143], v[0:15]
	v_add_f32_e32 v186, v186, v246
	v_add_f32_e32 v187, v187, v247
	s_mov_b64 s[8:9], -1
	s_cmp_lg_u32 s19, 0
	s_waitcnt lgkmcnt(0)
	s_barrier
	s_cbranch_scc1 .Lat2_reads
	s_branch .LBB0_319
